# phase1: Pcat table trips also pulled dynamically by all 8 waves
# speedup vs baseline: 1.0019x; 1.0019x over previous
.LBB0_71:
	s_or_b64 exec, exec, s[0:1]
	v_mov_b32_e32 v4, v193
	v_mov_b32_e32 v10, 0x20fe0
	v_mov_b32_e32 v11, 0
	ds_write2_b32 v10, v11, v11 offset1:1
	s_waitcnt lgkmcnt(0)
	s_barrier
	v_readlane_b32 s94, v248, 1
	v_readfirstlane_b32 s0, v4
	s_ashr_i32 s38, s0, 6
	v_and_b32_e32 v64, 63, v4
	s_cmp_gt_i32 s38, 3
	s_mov_b64 s[0:1], -1
	v_readlane_b32 s95, v248, 2
	s_cbranch_scc0 .LBB0_168
	s_lshl_b32 s0, s6, 2
	s_add_i32 s2, s38, -4
	s_add_i32 s94, s2, s0
	s_lshl_b32 s95, s92, 2
	s_cmpk_gt_i32 s94, 0x7ff
	s_cbranch_scc1 .LBB0_75
	s_mul_i32 s0, s2, 0x2400
	v_lshrrev_b32_e32 v5, 5, v64
	v_lshlrev_b32_e32 v1, 2, v4
	s_add_i32 s3, s0, 0
	v_mul_u32_u24_e32 v0, 0x84, v5
	v_and_b32_e32 v2, 0x7c, v1
	v_add3_u32 v6, s3, v0, v2
	v_lshlrev_b32_e32 v0, 3, v64
	v_lshrrev_b32_e32 v70, 3, v64
	v_and_b32_e32 v0, 56, v0
	v_mul_u32_u24_e32 v3, 0x84, v0
	v_lshlrev_b32_e32 v72, 1, v0
	v_mov_b32_e32 v73, 0
	v_lshlrev_b32_e32 v71, 2, v70
	v_lshl_add_u64 v[0:1], s[90:91], 0, v[72:73]
	s_mov_b64 s[0:1], 0x60000
	v_add3_u32 v71, s3, v3, v71
	v_mov_b32_e32 v3, v73
	v_or_b32_e32 v7, 2, v5
	v_add_u32_e32 v8, 0x108, v6
	v_or_b32_e32 v9, 4, v5
	v_add_u32_e32 v10, 0x210, v6
	v_or_b32_e32 v11, 6, v5
	v_add_u32_e32 v12, 0x318, v6
	v_or_b32_e32 v13, 8, v5
	v_add_u32_e32 v14, 0x420, v6
	v_or_b32_e32 v15, 10, v5
	v_add_u32_e32 v16, 0x528, v6
	v_or_b32_e32 v17, 12, v5
	v_add_u32_e32 v18, 0x630, v6
	v_or_b32_e32 v19, 14, v5
	v_add_u32_e32 v20, 0x738, v6
	v_or_b32_e32 v21, 16, v5
	v_add_u32_e32 v22, 0x840, v6
	v_or_b32_e32 v23, 18, v5
	v_add_u32_e32 v24, 0x948, v6
	v_or_b32_e32 v25, 20, v5
	v_add_u32_e32 v26, 0xa50, v6
	v_or_b32_e32 v27, 22, v5
	v_add_u32_e32 v28, 0xb58, v6
	v_or_b32_e32 v29, 24, v5
	v_add_u32_e32 v30, 0xc60, v6
	v_or_b32_e32 v31, 26, v5
	v_add_u32_e32 v32, 0xd68, v6
	v_or_b32_e32 v33, 28, v5
	v_add_u32_e32 v34, 0xe70, v6
	v_or_b32_e32 v35, 30, v5
	v_add_u32_e32 v36, 0xf78, v6
	v_or_b32_e32 v37, 32, v5
	v_add_u32_e32 v38, 0x1080, v6
	v_or_b32_e32 v39, 34, v5
	v_add_u32_e32 v40, 0x1188, v6
	v_or_b32_e32 v41, 36, v5
	v_add_u32_e32 v42, 0x1290, v6
	v_or_b32_e32 v43, 38, v5
	v_add_u32_e32 v44, 0x1398, v6
	v_or_b32_e32 v45, 40, v5
	v_add_u32_e32 v46, 0x14a0, v6
	v_or_b32_e32 v47, 42, v5
	v_add_u32_e32 v48, 0x15a8, v6
	v_or_b32_e32 v49, 44, v5
	v_add_u32_e32 v50, 0x16b0, v6
	v_or_b32_e32 v51, 46, v5
	v_add_u32_e32 v52, 0x17b8, v6
	v_or_b32_e32 v53, 48, v5
	v_add_u32_e32 v54, 0x18c0, v6
	v_or_b32_e32 v55, 50, v5
	v_add_u32_e32 v56, 0x19c8, v6
	v_or_b32_e32 v57, 52, v5
	v_add_u32_e32 v58, 0x1ad0, v6
	v_or_b32_e32 v59, 54, v5
	v_add_u32_e32 v60, 0x1bd8, v6
	v_or_b32_e32 v61, 56, v5
	v_add_u32_e32 v62, 0x1ce0, v6
	v_or_b32_e32 v63, 58, v5
	v_add_u32_e32 v65, 0x1de8, v6
	v_or_b32_e32 v66, 60, v5
	v_add_u32_e32 v67, 0x1ef0, v6
	v_or_b32_e32 v68, 62, v5
	v_add_u32_e32 v69, 0x1ff8, v6
	v_lshl_add_u64 v[0:1], v[0:1], 0, s[0:1]
	v_lshl_add_u64 v[2:3], s[48:49], 0, v[2:3]
	s_lshl_b32 s3, s94, 5
	s_lshl_b32 s7, s95, 5
	s_mov_b32 s8, s94

.Lmcat_done:
	s_mov_b64 s[0:1], -1
	v_mov_b32_e32 v6, 0
	s_branch .LBB0_164

.LBB0_164:
	s_or_b64 exec, exec, s[0:1]
	s_mov_b32 s0, 0x100000
	v_cmp_gt_i32_e32 vcc, s0, v6
	s_and_saveexec_b64 s[8:9], vcc
	s_cbranch_execz .LBB0_167
	s_add_u32 s10, s90, 0x3760000
	s_addc_u32 s11, s91, 0
	s_add_u32 s12, s90, 0x3fe0000
	s_addc_u32 s13, s91, 0
	s_add_u32 s14, s90, 0x40e8000
	s_addc_u32 s15, s91, 0
	s_lshl_b32 s2, s92, 9
	s_mul_i32 s3, s92, 0x300
	v_lshlrev_b32_e32 v2, 2, v6
	s_lshl_b32 s7, s92, 12
	s_mov_b64 s[16:17], 0
	v_mov_b32_e32 v1, 0
	s_mov_b32 s18, 0xfffff
	s_branch .Lpcat_fetch

.Lpcat_fetch:
	s_mov_b64 exec, 1
	v_mov_b32_e32 v10, 0x20fe4
	v_mov_b32_e32 v11, 1
	ds_add_rtn_u32 v10, v10, v11
	s_waitcnt lgkmcnt(0)
	v_readfirstlane_b32 s98, v10
	s_mov_b64 exec, -1
	s_nop 0
	s_cmp_ge_u32 s98, 16
	s_cbranch_scc1 .LBB0_167
	s_and_b32 s99, s98, 3
	s_lshr_b32 s98, s98, 2
	s_lshl_b32 s100, s6, 2
	s_add_i32 s99, s99, s100
	s_lshl_b32 s99, s99, 6
	s_lshl_b32 s98, s98, 18
	s_add_i32 s99, s99, s98
	v_or_b32_e32 v6, s99, v64
	v_lshlrev_b32_e32 v2, 2, v6
	s_branch .LBB0_166
